# rec_pass1 HGRN items: operand loads issued one item ahead into dead registers (attention item prefetches HGRN item 1, HGRN item 1 prefetches item 2)
# speedup vs baseline: 1.0226x; 1.0226x over previous
.LBB0_180:
	s_andn2_b64 vcc, exec, s[2:3]
	s_cbranch_vccnz .LBB0_305
	s_cmpk_gt_i32 s20, 0x4ff
	s_cbranch_scc1 .LBB0_305
	s_mov_b32 s101, -1
	s_ashr_i32 s25, s24, 31
	s_lshl_b64 s[2:3], s[24:25], 13
	s_add_u32 s82, s48, s2
	s_addc_u32 s83, s49, s3
	s_lshl_b32 s8, s24, 7
	s_cmp_gt_i32 s70, 7
	s_cselect_b64 s[30:31], -1, 0
	s_lshl_b32 s9, s20, 3
	s_lshl_b32 s10, s72, 3
	s_branch .LBB0_190

.LBB0_231:
	s_and_b64 vcc, exec, s[2:3]
	s_cbranch_vccz .LBB0_291
	v_mov_b32_e32 v0, v206
	s_addk_i32 s6, 0xfe00
	v_ashrrev_i32_e32 v0, 8, v0
	v_mov_b32_e32 v28, v206
	v_mov_b32_e32 v22, v206
	v_mov_b32_e32 v1, v206
	v_add_u32_e32 v16, s6, v0
	s_movk_i32 s2, 0x100
	v_bfe_u32 v17, v22, 6, 2
	v_ashrrev_i32_e32 v0, 9, v16
	v_cmp_gt_u32_e32 vcc, s2, v1
	v_xor_b32_e32 v1, 3, v17
	v_and_b32_e32 v26, 15, v22
	v_cndmask_b32_e32 v27, v1, v17, vcc
	v_ashrrev_i32_e32 v1, 31, v0
	v_lshlrev_b64 v[24:25], 13, v[0:1]
	v_lshlrev_b32_e32 v0, 6, v16
	s_movk_i32 s2, 0x1fc0
	v_lshlrev_b32_e32 v32, 4, v27
	v_and_or_b32 v20, v0, s2, v24
	v_or_b32_e32 v19, v32, v26
	v_or_b32_e32 v24, v20, v19
	v_mov_b64_e32 v[0:1], s[68:69]
	v_lshrrev_b32_e32 v2, 1, v16
	v_mad_u64_u32 v[0:1], s[2:3], v24, s13, v[0:1]
	v_and_b32_e32 v34, 0xc0, v2
	v_bfe_u32 v23, v22, 4, 2
	v_mad_i32_i24 v1, v25, s13, v1
	v_lshlrev_b32_e32 v176, 1, v34
	v_lshl_add_u64 v[0:1], v[0:1], 0, v[176:177]
	v_lshlrev_b32_e32 v2, 4, v23
	v_mov_b32_e32 v3, v177
	v_lshl_add_u64 v[0:1], v[0:1], 0, v[2:3]
	s_mov_b64 s[2:3], 0x3e80a00
	v_lshl_add_u64 v[2:3], v[0:1], 0, s[2:3]
	s_mov_b32 s2, 0x3e80000
	v_add_co_u32_e32 v0, vcc, s2, v0
	v_mov_b32_e32 v33, v206
	s_nop 0
	v_addc_co_u32_e32 v1, vcc, 0, v1, vcc
	s_nop 0
	v_mov_b64_e32 v[36:37], s[76:77]
	v_bfe_u32 v29, v33, 6, 2
	v_bfe_u32 v30, v33, 2, 6
	v_lshlrev_b32_e32 v8, 4, v33
	v_lshlrev_b32_e32 v18, 4, v29
	v_and_b32_e32 v31, 48, v8
	v_or_b32_e32 v8, v20, v30
	v_or_b32_e32 v20, v20, v18
	v_and_b32_e32 v21, 63, v33
	v_mad_u64_u32 v[8:9], s[2:3], v8, s13, v[36:37]
	v_mad_u64_u32 v[36:37], s[2:3], v20, s13, v[36:37]
	v_mad_i32_i24 v37, v25, s13, v37
	v_lshlrev_b32_e32 v38, 1, v21
	v_mov_b32_e32 v39, v177
	v_lshl_add_u64 v[36:37], v[36:37], 0, v[38:39]
	v_mad_i32_i24 v9, v25, s13, v9
	v_lshl_add_u64 v[52:53], v[36:37], 0, v[176:177]
	v_lshl_add_u64 v[8:9], v[8:9], 0, v[176:177]
	v_lshlrev_b32_e32 v10, 1, v31
	v_mov_b32_e32 v11, v177
	v_lshl_add_u64 v[8:9], v[8:9], 0, v[10:11]
	v_mov_b32_e32 v20, 0
	s_andn2_b64 vcc, exec, s[30:31]
	v_mov_b32_e32 v36, 0
	v_or_b32_e32 v62, v21, v34
	v_lshlrev_b32_e32 v62, 2, v62
	s_cmp_eq_u32 s101, s20
	s_cbranch_scc1 .Lpfh_have
	s_lshl_b32 s100, s20, 1
	s_addk_i32 s100, 0xfe00
	v_lshrrev_b32_e32 v234, 8, v206
	v_add_u32_e32 v234, s100, v234
	v_lshlrev_b32_e32 v235, 6, v234
	v_and_b32_e32 v235, 0x1fc0, v235
	v_lshrrev_b32_e32 v236, 9, v234
	v_lshl_or_b32 v235, v236, 13, v235
	v_bfe_u32 v236, v234, 7, 2
	v_lshlrev_b32_e32 v236, 7, v236
	v_bfe_u32 v237, v206, 6, 2
	v_lshl_add_u32 v238, v237, 4, v235
	v_mul_u32_u24_e32 v238, 0x1400, v238
	v_and_b32_e32 v239, 63, v206
	v_lshl_add_u32 v238, v239, 1, v238
	v_add_u32_e32 v238, v238, v236
	v_lshlrev_b32_e32 v240, 1, v236
	v_lshl_add_u32 v240, v239, 2, v240
	v_lshrrev_b32_e32 v239, 8, v206
	v_mul_u32_u24_e32 v239, 3, v239
	v_xor_b32_e32 v239, v239, v237
	v_lshl_add_u32 v239, v239, 4, v235
	v_and_b32_e32 v241, 15, v206
	v_or_b32_e32 v239, v239, v241
	v_mul_u32_u24_e32 v239, 0x1400, v239
	v_bfe_u32 v241, v206, 4, 2
	v_lshl_add_u32 v239, v241, 4, v239
	v_add_u32_e32 v239, v239, v236
	v_bfe_u32 v241, v206, 2, 6
	v_or_b32_e32 v241, v235, v241
	v_mul_u32_u24_e32 v241, 0x1400, v241
	v_and_b32_e32 v234, 3, v206
	v_lshl_add_u32 v241, v234, 5, v241
	v_add_u32_e32 v241, v241, v236
	global_load_dwordx4 v[188:191], v239, s[76:77] offset:2560
	global_load_dwordx4 v[192:195], v239, s[76:77] offset:2624
	global_load_dwordx4 v[196:199], v241, s[76:77] offset:2048
	global_load_dwordx4 v[200:203], v241, s[76:77] offset:2064
	global_load_ushort v204, v238, s[76:77] offset:1536
	v_add_u32_e32 v238, 0x1400, v238
	global_load_ushort v205, v238, s[76:77] offset:1536
	v_add_u32_e32 v238, 0x1400, v238
	global_load_ushort v186, v238, s[76:77] offset:1536
	v_add_u32_e32 v238, 0x1400, v238
	global_load_ushort v187, v238, s[76:77] offset:1536
	v_add_u32_e32 v238, 0x1400, v238
	global_load_ushort v220, v238, s[76:77] offset:1536
	v_add_u32_e32 v238, 0x1400, v238
	global_load_ushort v221, v238, s[76:77] offset:1536
	v_add_u32_e32 v238, 0x1400, v238
	global_load_ushort v222, v238, s[76:77] offset:1536
	v_add_u32_e32 v238, 0x1400, v238
	global_load_ushort v223, v238, s[76:77] offset:1536
	v_add_u32_e32 v238, 0x1400, v238
	global_load_ushort v224, v238, s[76:77] offset:1536
	v_add_u32_e32 v238, 0x1400, v238
	global_load_ushort v225, v238, s[76:77] offset:1536
	v_add_u32_e32 v238, 0x1400, v238
	global_load_ushort v226, v238, s[76:77] offset:1536
	v_add_u32_e32 v238, 0x1400, v238
	global_load_ushort v227, v238, s[76:77] offset:1536
	v_add_u32_e32 v238, 0x1400, v238
	global_load_ushort v228, v238, s[76:77] offset:1536
	v_add_u32_e32 v238, 0x1400, v238
	global_load_ushort v229, v238, s[76:77] offset:1536
	v_add_u32_e32 v238, 0x1400, v238
	global_load_ushort v230, v238, s[76:77] offset:1536
	v_add_u32_e32 v238, 0x1400, v238
	global_load_ushort v231, v238, s[76:77] offset:1536
	global_load_dword v232, v240, s[52:53]
	global_load_dword v233, v240, s[52:53] offset:1024
.Lpfh_have:
	s_waitcnt vmcnt(0)
	v_mov_b32_e32 v4, v188
	v_mov_b32_e32 v5, v189
	v_mov_b32_e32 v6, v190
	v_mov_b32_e32 v7, v191
	v_mov_b32_e32 v0, v192
	v_mov_b32_e32 v1, v193
	v_mov_b32_e32 v2, v194
	v_mov_b32_e32 v3, v195
	v_mov_b32_e32 v12, v196
	v_mov_b32_e32 v13, v197
	v_mov_b32_e32 v14, v198
	v_mov_b32_e32 v15, v199
	v_mov_b32_e32 v8, v200
	v_mov_b32_e32 v9, v201
	v_mov_b32_e32 v10, v202
	v_mov_b32_e32 v11, v203
	v_mov_b32_e32 v40, v204
	v_mov_b32_e32 v51, v205
	v_mov_b32_e32 v50, v186
	v_mov_b32_e32 v49, v187
	v_mov_b32_e32 v48, v220
	v_mov_b32_e32 v47, v221
	v_mov_b32_e32 v46, v222
	v_mov_b32_e32 v45, v223
	v_mov_b32_e32 v44, v224
	v_mov_b32_e32 v43, v225
	v_mov_b32_e32 v42, v226
	v_mov_b32_e32 v41, v227
	v_mov_b32_e32 v39, v228
	v_mov_b32_e32 v38, v229
	v_mov_b32_e32 v37, v230
	v_mov_b32_e32 v35, v231
	v_mov_b32_e32 v63, v232
	v_mov_b32_e32 v64, v233
	s_add_i32 s101, s20, s72
	s_cmpk_lt_i32 s101, 0x300
	s_cbranch_scc0 .Lpfh_none
	s_lshl_b32 s100, s101, 1
	s_addk_i32 s100, 0xfe00
	v_lshrrev_b32_e32 v234, 8, v206
	v_add_u32_e32 v234, s100, v234
	v_lshlrev_b32_e32 v235, 6, v234
	v_and_b32_e32 v235, 0x1fc0, v235
	v_lshrrev_b32_e32 v236, 9, v234
	v_lshl_or_b32 v235, v236, 13, v235
	v_bfe_u32 v236, v234, 7, 2
	v_lshlrev_b32_e32 v236, 7, v236
	v_bfe_u32 v237, v206, 6, 2
	v_lshl_add_u32 v238, v237, 4, v235
	v_mul_u32_u24_e32 v238, 0x1400, v238
	v_and_b32_e32 v239, 63, v206
	v_lshl_add_u32 v238, v239, 1, v238
	v_add_u32_e32 v238, v238, v236
	v_lshlrev_b32_e32 v240, 1, v236
	v_lshl_add_u32 v240, v239, 2, v240
	v_lshrrev_b32_e32 v239, 8, v206
	v_mul_u32_u24_e32 v239, 3, v239
	v_xor_b32_e32 v239, v239, v237
	v_lshl_add_u32 v239, v239, 4, v235
	v_and_b32_e32 v241, 15, v206
	v_or_b32_e32 v239, v239, v241
	v_mul_u32_u24_e32 v239, 0x1400, v239
	v_bfe_u32 v241, v206, 4, 2
	v_lshl_add_u32 v239, v241, 4, v239
	v_add_u32_e32 v239, v239, v236
	v_bfe_u32 v241, v206, 2, 6
	v_or_b32_e32 v241, v235, v241
	v_mul_u32_u24_e32 v241, 0x1400, v241
	v_and_b32_e32 v234, 3, v206
	v_lshl_add_u32 v241, v234, 5, v241
	v_add_u32_e32 v241, v241, v236
	global_load_dwordx4 v[188:191], v239, s[76:77] offset:2560
	global_load_dwordx4 v[192:195], v239, s[76:77] offset:2624
	global_load_dwordx4 v[196:199], v241, s[76:77] offset:2048
	global_load_dwordx4 v[200:203], v241, s[76:77] offset:2064
	global_load_ushort v204, v238, s[76:77] offset:1536
	v_add_u32_e32 v238, 0x1400, v238
	global_load_ushort v205, v238, s[76:77] offset:1536
	v_add_u32_e32 v238, 0x1400, v238
	global_load_ushort v186, v238, s[76:77] offset:1536
	v_add_u32_e32 v238, 0x1400, v238
	global_load_ushort v187, v238, s[76:77] offset:1536
	v_add_u32_e32 v238, 0x1400, v238
	global_load_ushort v220, v238, s[76:77] offset:1536
	v_add_u32_e32 v238, 0x1400, v238
	global_load_ushort v221, v238, s[76:77] offset:1536
	v_add_u32_e32 v238, 0x1400, v238
	global_load_ushort v222, v238, s[76:77] offset:1536
	v_add_u32_e32 v238, 0x1400, v238
	global_load_ushort v223, v238, s[76:77] offset:1536
	v_add_u32_e32 v238, 0x1400, v238
	global_load_ushort v224, v238, s[76:77] offset:1536
	v_add_u32_e32 v238, 0x1400, v238
	global_load_ushort v225, v238, s[76:77] offset:1536
	v_add_u32_e32 v238, 0x1400, v238
	global_load_ushort v226, v238, s[76:77] offset:1536
	v_add_u32_e32 v238, 0x1400, v238
	global_load_ushort v227, v238, s[76:77] offset:1536
	v_add_u32_e32 v238, 0x1400, v238
	global_load_ushort v228, v238, s[76:77] offset:1536
	v_add_u32_e32 v238, 0x1400, v238
	global_load_ushort v229, v238, s[76:77] offset:1536
	v_add_u32_e32 v238, 0x1400, v238
	global_load_ushort v230, v238, s[76:77] offset:1536
	v_add_u32_e32 v238, 0x1400, v238
	global_load_ushort v231, v238, s[76:77] offset:1536
	global_load_dword v232, v240, s[52:53]
	global_load_dword v233, v240, s[52:53] offset:1024
	s_branch .Lpfh_done
.Lpfh_none:
	s_mov_b32 s101, -1
.Lpfh_done:
	s_barrier
	s_cbranch_vccnz .LBB0_234
	v_mov_b32_e32 v36, v63
	v_mov_b32_e32 v34, v64
	s_mov_b32 s2, 0xf149f2ca
	v_max3_f32 v52, v36, s2, v34
	v_sub_f32_e32 v36, v36, v52
	v_sub_f32_e32 v34, v34, v52
	v_mul_f32_e32 v36, 0x3fb8aa3b, v36
	v_mul_f32_e32 v34, 0x3fb8aa3b, v34
	v_exp_f32_e32 v36, v36
	v_exp_f32_e32 v34, v34
	v_mov_b32_e32 v52, v177
	v_add_f32_e32 v53, 0, v36
	v_pk_add_f32 v[52:53], v[34:35], v[52:53] op_sel_hi:[0,1]
	v_div_scale_f32 v34, s[2:3], v53, v53, v52
	v_rcp_f32_e32 v36, v34
	v_div_scale_f32 v54, vcc, v52, v53, v52
	v_fma_f32 v55, -v34, v36, 1.0
	v_fmac_f32_e32 v36, v55, v36
	v_mul_f32_e32 v55, v54, v36
	v_fma_f32 v56, -v34, v55, v54
	v_fmac_f32_e32 v55, v56, v36
	v_fma_f32 v34, -v34, v55, v54
	v_div_fmas_f32 v34, v34, v36, v55
	v_div_fixup_f32 v36, v34, v53, v52

.LBB0_293:
	s_add_i32 s101, s20, s72
	s_cmpk_lt_i32 s101, 0x100
	s_cbranch_scc1 .Lpfa_none
	s_cmpk_lt_i32 s101, 0x300
	s_cbranch_scc0 .Lpfa_none
	s_lshl_b32 s100, s101, 1
	s_addk_i32 s100, 0xfe00
	v_lshrrev_b32_e32 v234, 8, v206
	v_add_u32_e32 v234, s100, v234
	v_lshlrev_b32_e32 v235, 6, v234
	v_and_b32_e32 v235, 0x1fc0, v235
	v_lshrrev_b32_e32 v236, 9, v234
	v_lshl_or_b32 v235, v236, 13, v235
	v_bfe_u32 v236, v234, 7, 2
	v_lshlrev_b32_e32 v236, 7, v236
	v_bfe_u32 v237, v206, 6, 2
	v_lshl_add_u32 v238, v237, 4, v235
	v_mul_u32_u24_e32 v238, 0x1400, v238
	v_and_b32_e32 v239, 63, v206
	v_lshl_add_u32 v238, v239, 1, v238
	v_add_u32_e32 v238, v238, v236
	v_lshlrev_b32_e32 v240, 1, v236
	v_lshl_add_u32 v240, v239, 2, v240
	v_lshrrev_b32_e32 v239, 8, v206
	v_mul_u32_u24_e32 v239, 3, v239
	v_xor_b32_e32 v239, v239, v237
	v_lshl_add_u32 v239, v239, 4, v235
	v_and_b32_e32 v241, 15, v206
	v_or_b32_e32 v239, v239, v241
	v_mul_u32_u24_e32 v239, 0x1400, v239
	v_bfe_u32 v241, v206, 4, 2
	v_lshl_add_u32 v239, v241, 4, v239
	v_add_u32_e32 v239, v239, v236
	v_bfe_u32 v241, v206, 2, 6
	v_or_b32_e32 v241, v235, v241
	v_mul_u32_u24_e32 v241, 0x1400, v241
	v_and_b32_e32 v234, 3, v206
	v_lshl_add_u32 v241, v234, 5, v241
	v_add_u32_e32 v241, v241, v236
	global_load_dwordx4 v[188:191], v239, s[76:77] offset:2560
	global_load_dwordx4 v[192:195], v239, s[76:77] offset:2624
	global_load_dwordx4 v[196:199], v241, s[76:77] offset:2048
	global_load_dwordx4 v[200:203], v241, s[76:77] offset:2064
	global_load_ushort v204, v238, s[76:77] offset:1536
	v_add_u32_e32 v238, 0x1400, v238
	global_load_ushort v205, v238, s[76:77] offset:1536
	v_add_u32_e32 v238, 0x1400, v238
	global_load_ushort v186, v238, s[76:77] offset:1536
	v_add_u32_e32 v238, 0x1400, v238
	global_load_ushort v187, v238, s[76:77] offset:1536
	v_add_u32_e32 v238, 0x1400, v238
	global_load_ushort v220, v238, s[76:77] offset:1536
	v_add_u32_e32 v238, 0x1400, v238
	global_load_ushort v221, v238, s[76:77] offset:1536
	v_add_u32_e32 v238, 0x1400, v238
	global_load_ushort v222, v238, s[76:77] offset:1536
	v_add_u32_e32 v238, 0x1400, v238
	global_load_ushort v223, v238, s[76:77] offset:1536
	v_add_u32_e32 v238, 0x1400, v238
	global_load_ushort v224, v238, s[76:77] offset:1536
	v_add_u32_e32 v238, 0x1400, v238
	global_load_ushort v225, v238, s[76:77] offset:1536
	v_add_u32_e32 v238, 0x1400, v238
	global_load_ushort v226, v238, s[76:77] offset:1536
	v_add_u32_e32 v238, 0x1400, v238
	global_load_ushort v227, v238, s[76:77] offset:1536
	v_add_u32_e32 v238, 0x1400, v238
	global_load_ushort v228, v238, s[76:77] offset:1536
	v_add_u32_e32 v238, 0x1400, v238
	global_load_ushort v229, v238, s[76:77] offset:1536
	v_add_u32_e32 v238, 0x1400, v238
	global_load_ushort v230, v238, s[76:77] offset:1536
	v_add_u32_e32 v238, 0x1400, v238
	global_load_ushort v231, v238, s[76:77] offset:1536
	global_load_dword v232, v240, s[52:53]
	global_load_dword v233, v240, s[52:53] offset:1024
	s_branch .Lpfa_done
